# two-ended top-k compaction fill (no count/scan/exchange when exactly 256 keys >= th); final pair hand-off on a dedicated LDS slot
# speedup vs baseline: 1.1197x; 1.0127x over previous
; __device__ __forceinline__ void attn_item(const Ptrs& P, unsigned char* lds, int b, int tq0, int tid) {
;     ...
;         unsigned th = 0u;
;     ...
;             const unsigned cand = th | (1u << bit); unsigned cnt = 0, oth;
.Lbis_mspin:
	ds_read_b32 v27, v37
	s_waitcnt lgkmcnt(0)
	v_readfirstlane_b32 s13, v27
	s_nop 3
	s_and_b32 s89, s13, 0xffff
	s_cmp_eq_u32 s89, s12
	s_cbranch_scc0 .Lbis_mspin
	s_lshr_b32 s13, s13, 16
	s_max_u32 s84, s84, s13
	s_mov_b32 s85, 0
	s_mov_b32 s96, 0
	s_mov_b32 s87, s74

; __device__ __forceinline__ void attn_item(const Ptrs& P, unsigned char* lds, int b, int tq0, int tid) {
;     ...
;             cnt += oth;
;             if (cnt >= 256u) th = cand;
;             if (cnt == 256u) break;
.Lbis_spin:
	ds_read_b32 v27, v37
	s_waitcnt lgkmcnt(0)
	v_readfirstlane_b32 s20, v27
	s_nop 3
	s_and_b32 s89, s20, 0xffff
	s_cmp_eq_u32 s89, s13
	s_cbranch_scc0 .Lbis_spin
	s_lshr_b32 s20, s20, 16
	s_add_i32 s78, s78, s20
	s_xor_b32 s87, s87, 4
	s_xor_b32 s88, s88, 4
	s_cmp_gt_u32 s78, 0xff
	s_cselect_b32 s85, s12, s85
	s_cselect_b32 s96, s78, s96
	s_cmp_eq_u32 s78, 0x100
	s_cbranch_scc1 .Lbis_done

; #define PAIR_XCHG(SLOT, TAG, MINE, OTHER) do { const unsigned tg_ = (seq << 8) | (unsigned)(TAG); if (lane == 0) xw[w * 4 + (SLOT)] = ((MINE) << 16) | tg_; \
;             unsigned v_; do { v_ = xw[(w ^ 1) * 4 + (SLOT)]; } while ((v_ & 0xffffu) != tg_); OTHER = v_ >> 16; } while (0)
; __device__ __forceinline__ void attn_item(const Ptrs& P, unsigned char* lds, int b, int tq0, int tid) {
;     ...
;         unsigned cg = 0, ce = 0;
; #pragma unroll
;         for (int k = 0; k < 4; ++k) if (16 * k < nact) {
; #pragma unroll
;             for (int r = 16 * k; r < 16 * k + 16; ++r) { cg += (k2[r] > th) ? 1u : 0u; ce += (k2[r] == th) ? 1u : 0u; } }
;         const unsigned ig = wave_incl_scan(cg, lane), ie = wave_incl_scan(ce, lane);
;         const unsigned ngt = (unsigned)__builtin_amdgcn_readlane((int)ig, 63), neq = (unsigned)__builtin_amdgcn_readlane((int)ie, 63);
;         unsigned ogt, oeq;
;         PAIR_XCHG(2, 40, ngt, ogt); PAIR_XCHG(3, 41, neq, oeq);
;         const unsigned tot_gt = ngt + ogt, quota = 256u - tot_gt;
;         unsigned pos_g = (hs ? ogt : 0u) + ig - cg, pos_e = (hs ? oeq : 0u) + ie - ce;
;         const bool any_eq = (neq + oeq) != 0u;
; #pragma unroll
;         for (int k = 0; k < 4; ++k) if (16 * k < nact) {
; #pragma unroll
;             for (int r = 16 * k; r < 16 * k + 16; ++r) { const unsigned short idx = (unsigned short)(64 * (2 * r + hs) + lane);
;                 if (k2[r] > th) { sel[qs * 256 + pos_g] = idx; ++pos_g; }
;                 if (any_eq) { if (k2[r] == th) { if (pos_e < quota) sel[qs * 256 + tot_gt + pos_e] = idx; ++pos_e; } } } }
.Lbis_done:
	v_mov_b32_e32 v5, s85
	s_cmp_lg_u32 s96, 0x100
	s_cbranch_scc1 .Lcmp_slow
	s_mov_b64 s[44:45], exec
	s_mov_b64 s[92:93], vcc
	s_lshl_b32 s20, s65, 9
	s_add_i32 s20, s20, 0x21000
	s_lshl_b32 s12, s64, 6
	v_or_b32_e32 v29, s12, v179
	s_add_i32 s12, s20, 0x1fe
	s_cmp_eq_u32 s64, 0
	s_cselect_b32 s88, 2, -2
	s_cselect_b32 s87, s20, s12
	v_mov_b32_e32 v38, s88
	s_xor_b32 s12, s83, 4
	s_lshl_b32 s12, s12, 2
	s_add_i32 s72, s12, 0x24000
	s_cmp_eq_u64 s[18:19], 0
	s_cbranch_scc1 .Lcmp2_done
	v_cmp_ge_u32_e64 s[78:79], v6, v5
	v_cmp_ge_u32_e64 s[90:91], v95, v5
	s_nop 0
	v_mbcnt_lo_u32_b32 v37, s78, 0
	v_mbcnt_hi_u32_b32 v37, s79, v37
	v_mad_i32_i24 v36, v37, v38, s87
	s_mov_b64 exec, s[78:79]
	ds_write_b16 v36, v29
	s_mov_b64 exec, s[44:45]
	s_bcnt1_i32_b64 s12, s[78:79]
	s_mul_i32 s12, s12, s88
	s_add_i32 s87, s87, s12
	v_cmp_ge_u32_e64 s[78:79], v94, v5
	v_or_b32_e32 v39, 0x80, v29
	v_mbcnt_lo_u32_b32 v37, s90, 0
	v_mbcnt_hi_u32_b32 v37, s91, v37
	v_mad_i32_i24 v36, v37, v38, s87
	s_mov_b64 exec, s[90:91]
	ds_write_b16 v36, v39
	s_mov_b64 exec, s[44:45]
	s_bcnt1_i32_b64 s12, s[90:91]
	s_mul_i32 s12, s12, s88
	s_add_i32 s87, s87, s12
	v_cmp_ge_u32_e64 s[90:91], v93, v5
	v_or_b32_e32 v39, 0x100, v29
	v_mbcnt_lo_u32_b32 v37, s78, 0
	v_mbcnt_hi_u32_b32 v37, s79, v37
	v_mad_i32_i24 v36, v37, v38, s87
	s_mov_b64 exec, s[78:79]
	ds_write_b16 v36, v39
	s_mov_b64 exec, s[44:45]
	s_bcnt1_i32_b64 s12, s[78:79]
	s_mul_i32 s12, s12, s88
	s_add_i32 s87, s87, s12
	v_cmp_ge_u32_e64 s[78:79], v92, v5
	v_or_b32_e32 v39, 0x180, v29
	v_mbcnt_lo_u32_b32 v37, s90, 0
	v_mbcnt_hi_u32_b32 v37, s91, v37
	v_mad_i32_i24 v36, v37, v38, s87
	s_mov_b64 exec, s[90:91]
	ds_write_b16 v36, v39
	s_mov_b64 exec, s[44:45]
	s_bcnt1_i32_b64 s12, s[90:91]
	s_mul_i32 s12, s12, s88
	s_add_i32 s87, s87, s12
	v_cmp_ge_u32_e64 s[90:91], v91, v5
	v_or_b32_e32 v39, 0x200, v29
	v_mbcnt_lo_u32_b32 v37, s78, 0
	v_mbcnt_hi_u32_b32 v37, s79, v37
	v_mad_i32_i24 v36, v37, v38, s87
	s_mov_b64 exec, s[78:79]
	ds_write_b16 v36, v39
	s_mov_b64 exec, s[44:45]
	s_bcnt1_i32_b64 s12, s[78:79]
	s_mul_i32 s12, s12, s88
	s_add_i32 s87, s87, s12
	v_cmp_ge_u32_e64 s[78:79], v90, v5
	v_or_b32_e32 v39, 0x280, v29
	v_mbcnt_lo_u32_b32 v37, s90, 0
	v_mbcnt_hi_u32_b32 v37, s91, v37
	v_mad_i32_i24 v36, v37, v38, s87
	s_mov_b64 exec, s[90:91]
	ds_write_b16 v36, v39
	s_mov_b64 exec, s[44:45]
	s_bcnt1_i32_b64 s12, s[90:91]
	s_mul_i32 s12, s12, s88
	s_add_i32 s87, s87, s12
	v_cmp_ge_u32_e64 s[90:91], v89, v5
	v_or_b32_e32 v39, 0x300, v29
	v_mbcnt_lo_u32_b32 v37, s78, 0
	v_mbcnt_hi_u32_b32 v37, s79, v37
	v_mad_i32_i24 v36, v37, v38, s87
	s_mov_b64 exec, s[78:79]
	ds_write_b16 v36, v39
	s_mov_b64 exec, s[44:45]
	s_bcnt1_i32_b64 s12, s[78:79]
	s_mul_i32 s12, s12, s88
	s_add_i32 s87, s87, s12
	v_cmp_ge_u32_e64 s[78:79], v88, v5
	v_or_b32_e32 v39, 0x380, v29
	v_mbcnt_lo_u32_b32 v37, s90, 0
	v_mbcnt_hi_u32_b32 v37, s91, v37
	v_mad_i32_i24 v36, v37, v38, s87
	s_mov_b64 exec, s[90:91]
	ds_write_b16 v36, v39
	s_mov_b64 exec, s[44:45]
	s_bcnt1_i32_b64 s12, s[90:91]
	s_mul_i32 s12, s12, s88
	s_add_i32 s87, s87, s12
	v_cmp_ge_u32_e64 s[90:91], v87, v5
	v_or_b32_e32 v39, 0x400, v29
	v_mbcnt_lo_u32_b32 v37, s78, 0
	v_mbcnt_hi_u32_b32 v37, s79, v37
	v_mad_i32_i24 v36, v37, v38, s87
	s_mov_b64 exec, s[78:79]
	ds_write_b16 v36, v39
	s_mov_b64 exec, s[44:45]
	s_bcnt1_i32_b64 s12, s[78:79]
	s_mul_i32 s12, s12, s88
	s_add_i32 s87, s87, s12
	v_cmp_ge_u32_e64 s[78:79], v86, v5
	v_or_b32_e32 v39, 0x480, v29
	v_mbcnt_lo_u32_b32 v37, s90, 0
	v_mbcnt_hi_u32_b32 v37, s91, v37
	v_mad_i32_i24 v36, v37, v38, s87
	s_mov_b64 exec, s[90:91]
	ds_write_b16 v36, v39
	s_mov_b64 exec, s[44:45]
	s_bcnt1_i32_b64 s12, s[90:91]
	s_mul_i32 s12, s12, s88
	s_add_i32 s87, s87, s12
	v_cmp_ge_u32_e64 s[90:91], v85, v5
	v_or_b32_e32 v39, 0x500, v29
	v_mbcnt_lo_u32_b32 v37, s78, 0
	v_mbcnt_hi_u32_b32 v37, s79, v37
	v_mad_i32_i24 v36, v37, v38, s87
	s_mov_b64 exec, s[78:79]
	ds_write_b16 v36, v39
	s_mov_b64 exec, s[44:45]
	s_bcnt1_i32_b64 s12, s[78:79]
	s_mul_i32 s12, s12, s88
	s_add_i32 s87, s87, s12
	v_cmp_ge_u32_e64 s[78:79], v84, v5
	v_or_b32_e32 v39, 0x580, v29
	v_mbcnt_lo_u32_b32 v37, s90, 0
	v_mbcnt_hi_u32_b32 v37, s91, v37
	v_mad_i32_i24 v36, v37, v38, s87
	s_mov_b64 exec, s[90:91]
	ds_write_b16 v36, v39
	s_mov_b64 exec, s[44:45]
	s_bcnt1_i32_b64 s12, s[90:91]
	s_mul_i32 s12, s12, s88
	s_add_i32 s87, s87, s12
	v_cmp_ge_u32_e64 s[90:91], v83, v5
	v_or_b32_e32 v39, 0x600, v29
	v_mbcnt_lo_u32_b32 v37, s78, 0
	v_mbcnt_hi_u32_b32 v37, s79, v37
	v_mad_i32_i24 v36, v37, v38, s87
	s_mov_b64 exec, s[78:79]
	ds_write_b16 v36, v39
	s_mov_b64 exec, s[44:45]
	s_bcnt1_i32_b64 s12, s[78:79]
	s_mul_i32 s12, s12, s88
	s_add_i32 s87, s87, s12
	v_cmp_ge_u32_e64 s[78:79], v82, v5
	v_or_b32_e32 v39, 0x680, v29
	v_mbcnt_lo_u32_b32 v37, s90, 0
	v_mbcnt_hi_u32_b32 v37, s91, v37
	v_mad_i32_i24 v36, v37, v38, s87
	s_mov_b64 exec, s[90:91]
	ds_write_b16 v36, v39
	s_mov_b64 exec, s[44:45]
	s_bcnt1_i32_b64 s12, s[90:91]
	s_mul_i32 s12, s12, s88
	s_add_i32 s87, s87, s12
	v_cmp_ge_u32_e64 s[90:91], v81, v5
	v_or_b32_e32 v39, 0x700, v29
	v_mbcnt_lo_u32_b32 v37, s78, 0
	v_mbcnt_hi_u32_b32 v37, s79, v37
	v_mad_i32_i24 v36, v37, v38, s87
	s_mov_b64 exec, s[78:79]
	ds_write_b16 v36, v39
	s_mov_b64 exec, s[44:45]
	s_bcnt1_i32_b64 s12, s[78:79]
	s_mul_i32 s12, s12, s88
	s_add_i32 s87, s87, s12
	v_or_b32_e32 v39, 0x780, v29
	s_nop 0
	v_mbcnt_lo_u32_b32 v37, s90, 0
	v_mbcnt_hi_u32_b32 v37, s91, v37
	v_mad_i32_i24 v36, v37, v38, s87
	s_mov_b64 exec, s[90:91]
	ds_write_b16 v36, v39
	s_mov_b64 exec, s[44:45]
	s_bcnt1_i32_b64 s12, s[90:91]
	s_mul_i32 s12, s12, s88
	s_add_i32 s87, s87, s12
	s_cmp_eq_u64 s[16:17], 0
	s_cbranch_scc1 .Lcmp2_done
; __device__ __forceinline__ void attn_item(const Ptrs& P, unsigned char* lds, int b, int tq0, int tid) {
;     ...
; #pragma unroll
;         for (int k = 0; k < 4; ++k) if (16 * k < nact) {
; #pragma unroll
;             for (int r = 16 * k; r < 16 * k + 16; ++r) { const unsigned short idx = (unsigned short)(64 * (2 * r + hs) + lane);
;                 if (k2[r] > th) { sel[qs * 256 + pos_g] = idx; ++pos_g; }
;                 if (any_eq) { if (k2[r] == th) { if (pos_e < quota) sel[qs * 256 + tot_gt + pos_e] = idx; ++pos_e; } } } }
	v_cmp_ge_u32_e64 s[78:79], v4, v5
	v_cmp_ge_u32_e64 s[90:91], v80, v5
	v_or_b32_e32 v39, 0x800, v29
	v_mbcnt_lo_u32_b32 v37, s78, 0
	v_mbcnt_hi_u32_b32 v37, s79, v37
	v_mad_i32_i24 v36, v37, v38, s87
	s_mov_b64 exec, s[78:79]
	ds_write_b16 v36, v39
	s_mov_b64 exec, s[44:45]
	s_bcnt1_i32_b64 s12, s[78:79]
	s_mul_i32 s12, s12, s88
	s_add_i32 s87, s87, s12
	v_cmp_ge_u32_e64 s[78:79], v79, v5
	v_or_b32_e32 v39, 0x880, v29
	v_mbcnt_lo_u32_b32 v37, s90, 0
	v_mbcnt_hi_u32_b32 v37, s91, v37
	v_mad_i32_i24 v36, v37, v38, s87
	s_mov_b64 exec, s[90:91]
	ds_write_b16 v36, v39
	s_mov_b64 exec, s[44:45]
	s_bcnt1_i32_b64 s12, s[90:91]
	s_mul_i32 s12, s12, s88
	s_add_i32 s87, s87, s12
	v_cmp_ge_u32_e64 s[90:91], v78, v5
	v_or_b32_e32 v39, 0x900, v29
	v_mbcnt_lo_u32_b32 v37, s78, 0
	v_mbcnt_hi_u32_b32 v37, s79, v37
	v_mad_i32_i24 v36, v37, v38, s87
	s_mov_b64 exec, s[78:79]
	ds_write_b16 v36, v39
	s_mov_b64 exec, s[44:45]
	s_bcnt1_i32_b64 s12, s[78:79]
	s_mul_i32 s12, s12, s88
	s_add_i32 s87, s87, s12
	v_cmp_ge_u32_e64 s[78:79], v77, v5
	v_or_b32_e32 v39, 0x980, v29
	v_mbcnt_lo_u32_b32 v37, s90, 0
	v_mbcnt_hi_u32_b32 v37, s91, v37
	v_mad_i32_i24 v36, v37, v38, s87
	s_mov_b64 exec, s[90:91]
	ds_write_b16 v36, v39
	s_mov_b64 exec, s[44:45]
	s_bcnt1_i32_b64 s12, s[90:91]
	s_mul_i32 s12, s12, s88
	s_add_i32 s87, s87, s12
	v_cmp_ge_u32_e64 s[90:91], v76, v5
	v_or_b32_e32 v39, 0xa00, v29
	v_mbcnt_lo_u32_b32 v37, s78, 0
	v_mbcnt_hi_u32_b32 v37, s79, v37
	v_mad_i32_i24 v36, v37, v38, s87
	s_mov_b64 exec, s[78:79]
	ds_write_b16 v36, v39
	s_mov_b64 exec, s[44:45]
	s_bcnt1_i32_b64 s12, s[78:79]
	s_mul_i32 s12, s12, s88
	s_add_i32 s87, s87, s12
	v_cmp_ge_u32_e64 s[78:79], v75, v5
	v_or_b32_e32 v39, 0xa80, v29
	v_mbcnt_lo_u32_b32 v37, s90, 0
	v_mbcnt_hi_u32_b32 v37, s91, v37
	v_mad_i32_i24 v36, v37, v38, s87
	s_mov_b64 exec, s[90:91]
	ds_write_b16 v36, v39
	s_mov_b64 exec, s[44:45]
	s_bcnt1_i32_b64 s12, s[90:91]
	s_mul_i32 s12, s12, s88
	s_add_i32 s87, s87, s12
	v_cmp_ge_u32_e64 s[90:91], v74, v5
	v_or_b32_e32 v39, 0xb00, v29
	v_mbcnt_lo_u32_b32 v37, s78, 0
	v_mbcnt_hi_u32_b32 v37, s79, v37
	v_mad_i32_i24 v36, v37, v38, s87
	s_mov_b64 exec, s[78:79]
	ds_write_b16 v36, v39
	s_mov_b64 exec, s[44:45]
	s_bcnt1_i32_b64 s12, s[78:79]
	s_mul_i32 s12, s12, s88
	s_add_i32 s87, s87, s12
	v_cmp_ge_u32_e64 s[78:79], v73, v5
	v_or_b32_e32 v39, 0xb80, v29
	v_mbcnt_lo_u32_b32 v37, s90, 0
	v_mbcnt_hi_u32_b32 v37, s91, v37
	v_mad_i32_i24 v36, v37, v38, s87
	s_mov_b64 exec, s[90:91]
	ds_write_b16 v36, v39
	s_mov_b64 exec, s[44:45]
	s_bcnt1_i32_b64 s12, s[90:91]
	s_mul_i32 s12, s12, s88
	s_add_i32 s87, s87, s12
	v_cmp_ge_u32_e64 s[90:91], v72, v5
	v_or_b32_e32 v39, 0xc00, v29
	v_mbcnt_lo_u32_b32 v37, s78, 0
	v_mbcnt_hi_u32_b32 v37, s79, v37
	v_mad_i32_i24 v36, v37, v38, s87
	s_mov_b64 exec, s[78:79]
	ds_write_b16 v36, v39
	s_mov_b64 exec, s[44:45]
	s_bcnt1_i32_b64 s12, s[78:79]
	s_mul_i32 s12, s12, s88
	s_add_i32 s87, s87, s12
	v_cmp_ge_u32_e64 s[78:79], v71, v5
	v_or_b32_e32 v39, 0xc80, v29
	v_mbcnt_lo_u32_b32 v37, s90, 0
	v_mbcnt_hi_u32_b32 v37, s91, v37
	v_mad_i32_i24 v36, v37, v38, s87
	s_mov_b64 exec, s[90:91]
	ds_write_b16 v36, v39
	s_mov_b64 exec, s[44:45]
	s_bcnt1_i32_b64 s12, s[90:91]
	s_mul_i32 s12, s12, s88
	s_add_i32 s87, s87, s12
	v_cmp_ge_u32_e64 s[90:91], v70, v5
	v_or_b32_e32 v39, 0xd00, v29
	v_mbcnt_lo_u32_b32 v37, s78, 0
	v_mbcnt_hi_u32_b32 v37, s79, v37
	v_mad_i32_i24 v36, v37, v38, s87
	s_mov_b64 exec, s[78:79]
	ds_write_b16 v36, v39
	s_mov_b64 exec, s[44:45]
	s_bcnt1_i32_b64 s12, s[78:79]
	s_mul_i32 s12, s12, s88
	s_add_i32 s87, s87, s12
	v_cmp_ge_u32_e64 s[78:79], v69, v5
	v_or_b32_e32 v39, 0xd80, v29
	v_mbcnt_lo_u32_b32 v37, s90, 0
	v_mbcnt_hi_u32_b32 v37, s91, v37
	v_mad_i32_i24 v36, v37, v38, s87
	s_mov_b64 exec, s[90:91]
	ds_write_b16 v36, v39
	s_mov_b64 exec, s[44:45]
	s_bcnt1_i32_b64 s12, s[90:91]
	s_mul_i32 s12, s12, s88
	s_add_i32 s87, s87, s12
	v_cmp_ge_u32_e64 s[90:91], v68, v5
	v_or_b32_e32 v39, 0xe00, v29
	v_mbcnt_lo_u32_b32 v37, s78, 0
	v_mbcnt_hi_u32_b32 v37, s79, v37
	v_mad_i32_i24 v36, v37, v38, s87
	s_mov_b64 exec, s[78:79]
	ds_write_b16 v36, v39
	s_mov_b64 exec, s[44:45]
	s_bcnt1_i32_b64 s12, s[78:79]
	s_mul_i32 s12, s12, s88
	s_add_i32 s87, s87, s12
	v_cmp_ge_u32_e64 s[78:79], v67, v5
	v_or_b32_e32 v39, 0xe80, v29
	v_mbcnt_lo_u32_b32 v37, s90, 0
	v_mbcnt_hi_u32_b32 v37, s91, v37
	v_mad_i32_i24 v36, v37, v38, s87
	s_mov_b64 exec, s[90:91]
	ds_write_b16 v36, v39
	s_mov_b64 exec, s[44:45]
	s_bcnt1_i32_b64 s12, s[90:91]
	s_mul_i32 s12, s12, s88
	s_add_i32 s87, s87, s12
	v_cmp_ge_u32_e64 s[90:91], v66, v5
	v_or_b32_e32 v39, 0xf00, v29
	v_mbcnt_lo_u32_b32 v37, s78, 0
	v_mbcnt_hi_u32_b32 v37, s79, v37
	v_mad_i32_i24 v36, v37, v38, s87
	s_mov_b64 exec, s[78:79]
	ds_write_b16 v36, v39
	s_mov_b64 exec, s[44:45]
	s_bcnt1_i32_b64 s12, s[78:79]
	s_mul_i32 s12, s12, s88
	s_add_i32 s87, s87, s12
	v_or_b32_e32 v39, 0xf80, v29
	s_nop 0
	v_mbcnt_lo_u32_b32 v37, s90, 0
	v_mbcnt_hi_u32_b32 v37, s91, v37
	v_mad_i32_i24 v36, v37, v38, s87
	s_mov_b64 exec, s[90:91]
	ds_write_b16 v36, v39
	s_mov_b64 exec, s[44:45]
	s_bcnt1_i32_b64 s12, s[90:91]
	s_mul_i32 s12, s12, s88
	s_add_i32 s87, s87, s12
	s_cmp_eq_u64 s[14:15], 0
	s_cbranch_scc1 .Lcmp2_done
; __device__ __forceinline__ void attn_item(const Ptrs& P, unsigned char* lds, int b, int tq0, int tid) {
;     ...
; #pragma unroll
;         for (int k = 0; k < 4; ++k) if (16 * k < nact) {
; #pragma unroll
;             for (int r = 16 * k; r < 16 * k + 16; ++r) { const unsigned short idx = (unsigned short)(64 * (2 * r + hs) + lane);
;                 if (k2[r] > th) { sel[qs * 256 + pos_g] = idx; ++pos_g; }
;                 if (any_eq) { if (k2[r] == th) { if (pos_e < quota) sel[qs * 256 + tot_gt + pos_e] = idx; ++pos_e; } } } }
	v_cmp_ge_u32_e64 s[78:79], v2, v5
	v_cmp_ge_u32_e64 s[90:91], v65, v5
	v_or_b32_e32 v39, 0x1000, v29
	v_mbcnt_lo_u32_b32 v37, s78, 0
	v_mbcnt_hi_u32_b32 v37, s79, v37
	v_mad_i32_i24 v36, v37, v38, s87
	s_mov_b64 exec, s[78:79]
	ds_write_b16 v36, v39
	s_mov_b64 exec, s[44:45]
	s_bcnt1_i32_b64 s12, s[78:79]
	s_mul_i32 s12, s12, s88
	s_add_i32 s87, s87, s12
	v_cmp_ge_u32_e64 s[78:79], v64, v5
	v_or_b32_e32 v39, 0x1080, v29
	v_mbcnt_lo_u32_b32 v37, s90, 0
	v_mbcnt_hi_u32_b32 v37, s91, v37
	v_mad_i32_i24 v36, v37, v38, s87
	s_mov_b64 exec, s[90:91]
	ds_write_b16 v36, v39
	s_mov_b64 exec, s[44:45]
	s_bcnt1_i32_b64 s12, s[90:91]
	s_mul_i32 s12, s12, s88
	s_add_i32 s87, s87, s12
	v_cmp_ge_u32_e64 s[90:91], v49, v5
	v_or_b32_e32 v39, 0x1100, v29
	v_mbcnt_lo_u32_b32 v37, s78, 0
	v_mbcnt_hi_u32_b32 v37, s79, v37
	v_mad_i32_i24 v36, v37, v38, s87
	s_mov_b64 exec, s[78:79]
	ds_write_b16 v36, v39
	s_mov_b64 exec, s[44:45]
	s_bcnt1_i32_b64 s12, s[78:79]
	s_mul_i32 s12, s12, s88
	s_add_i32 s87, s87, s12
	v_cmp_ge_u32_e64 s[78:79], v48, v5
	v_or_b32_e32 v39, 0x1180, v29
	v_mbcnt_lo_u32_b32 v37, s90, 0
	v_mbcnt_hi_u32_b32 v37, s91, v37
	v_mad_i32_i24 v36, v37, v38, s87
	s_mov_b64 exec, s[90:91]
	ds_write_b16 v36, v39
	s_mov_b64 exec, s[44:45]
	s_bcnt1_i32_b64 s12, s[90:91]
	s_mul_i32 s12, s12, s88
	s_add_i32 s87, s87, s12
	v_cmp_ge_u32_e64 s[90:91], v46, v5
	v_or_b32_e32 v39, 0x1200, v29
	v_mbcnt_lo_u32_b32 v37, s78, 0
	v_mbcnt_hi_u32_b32 v37, s79, v37
	v_mad_i32_i24 v36, v37, v38, s87
	s_mov_b64 exec, s[78:79]
	ds_write_b16 v36, v39
	s_mov_b64 exec, s[44:45]
	s_bcnt1_i32_b64 s12, s[78:79]
	s_mul_i32 s12, s12, s88
	s_add_i32 s87, s87, s12
	v_cmp_ge_u32_e64 s[78:79], v35, v5
	v_or_b32_e32 v39, 0x1280, v29
	v_mbcnt_lo_u32_b32 v37, s90, 0
	v_mbcnt_hi_u32_b32 v37, s91, v37
	v_mad_i32_i24 v36, v37, v38, s87
	s_mov_b64 exec, s[90:91]
	ds_write_b16 v36, v39
	s_mov_b64 exec, s[44:45]
	s_bcnt1_i32_b64 s12, s[90:91]
	s_mul_i32 s12, s12, s88
	s_add_i32 s87, s87, s12
	v_cmp_ge_u32_e64 s[90:91], v34, v5
	v_or_b32_e32 v39, 0x1300, v29
	v_mbcnt_lo_u32_b32 v37, s78, 0
	v_mbcnt_hi_u32_b32 v37, s79, v37
	v_mad_i32_i24 v36, v37, v38, s87
	s_mov_b64 exec, s[78:79]
	ds_write_b16 v36, v39
	s_mov_b64 exec, s[44:45]
	s_bcnt1_i32_b64 s12, s[78:79]
	s_mul_i32 s12, s12, s88
	s_add_i32 s87, s87, s12
	v_cmp_ge_u32_e64 s[78:79], v33, v5
	v_or_b32_e32 v39, 0x1380, v29
	v_mbcnt_lo_u32_b32 v37, s90, 0
	v_mbcnt_hi_u32_b32 v37, s91, v37
	v_mad_i32_i24 v36, v37, v38, s87
	s_mov_b64 exec, s[90:91]
	ds_write_b16 v36, v39
	s_mov_b64 exec, s[44:45]
	s_bcnt1_i32_b64 s12, s[90:91]
	s_mul_i32 s12, s12, s88
	s_add_i32 s87, s87, s12
	v_cmp_ge_u32_e64 s[90:91], v32, v5
	v_or_b32_e32 v39, 0x1400, v29
	v_mbcnt_lo_u32_b32 v37, s78, 0
	v_mbcnt_hi_u32_b32 v37, s79, v37
	v_mad_i32_i24 v36, v37, v38, s87
	s_mov_b64 exec, s[78:79]
	ds_write_b16 v36, v39
	s_mov_b64 exec, s[44:45]
	s_bcnt1_i32_b64 s12, s[78:79]
	s_mul_i32 s12, s12, s88
	s_add_i32 s87, s87, s12
	v_cmp_ge_u32_e64 s[78:79], v31, v5
	v_or_b32_e32 v39, 0x1480, v29
	v_mbcnt_lo_u32_b32 v37, s90, 0
	v_mbcnt_hi_u32_b32 v37, s91, v37
	v_mad_i32_i24 v36, v37, v38, s87
	s_mov_b64 exec, s[90:91]
	ds_write_b16 v36, v39
	s_mov_b64 exec, s[44:45]
	s_bcnt1_i32_b64 s12, s[90:91]
	s_mul_i32 s12, s12, s88
	s_add_i32 s87, s87, s12
	v_cmp_ge_u32_e64 s[90:91], v30, v5
	v_or_b32_e32 v39, 0x1500, v29
	v_mbcnt_lo_u32_b32 v37, s78, 0
	v_mbcnt_hi_u32_b32 v37, s79, v37
	v_mad_i32_i24 v36, v37, v38, s87
	s_mov_b64 exec, s[78:79]
	ds_write_b16 v36, v39
	s_mov_b64 exec, s[44:45]
	s_bcnt1_i32_b64 s12, s[78:79]
	s_mul_i32 s12, s12, s88
	s_add_i32 s87, s87, s12
	v_cmp_ge_u32_e64 s[78:79], v28, v5
	v_or_b32_e32 v39, 0x1580, v29
	v_mbcnt_lo_u32_b32 v37, s90, 0
	v_mbcnt_hi_u32_b32 v37, s91, v37
	v_mad_i32_i24 v36, v37, v38, s87
	s_mov_b64 exec, s[90:91]
	ds_write_b16 v36, v39
	s_mov_b64 exec, s[44:45]
	s_bcnt1_i32_b64 s12, s[90:91]
	s_mul_i32 s12, s12, s88
	s_add_i32 s87, s87, s12
	v_cmp_ge_u32_e64 s[90:91], v23, v5
	v_or_b32_e32 v39, 0x1600, v29
	v_mbcnt_lo_u32_b32 v37, s78, 0
	v_mbcnt_hi_u32_b32 v37, s79, v37
	v_mad_i32_i24 v36, v37, v38, s87
	s_mov_b64 exec, s[78:79]
	ds_write_b16 v36, v39
	s_mov_b64 exec, s[44:45]
	s_bcnt1_i32_b64 s12, s[78:79]
	s_mul_i32 s12, s12, s88
	s_add_i32 s87, s87, s12
	v_cmp_ge_u32_e64 s[78:79], v22, v5
	v_or_b32_e32 v39, 0x1680, v29
	v_mbcnt_lo_u32_b32 v37, s90, 0
	v_mbcnt_hi_u32_b32 v37, s91, v37
	v_mad_i32_i24 v36, v37, v38, s87
	s_mov_b64 exec, s[90:91]
	ds_write_b16 v36, v39
	s_mov_b64 exec, s[44:45]
	s_bcnt1_i32_b64 s12, s[90:91]
	s_mul_i32 s12, s12, s88
	s_add_i32 s87, s87, s12
	v_cmp_ge_u32_e64 s[90:91], v21, v5
	v_or_b32_e32 v39, 0x1700, v29
	v_mbcnt_lo_u32_b32 v37, s78, 0
	v_mbcnt_hi_u32_b32 v37, s79, v37
	v_mad_i32_i24 v36, v37, v38, s87
	s_mov_b64 exec, s[78:79]
	ds_write_b16 v36, v39
	s_mov_b64 exec, s[44:45]
	s_bcnt1_i32_b64 s12, s[78:79]
	s_mul_i32 s12, s12, s88
	s_add_i32 s87, s87, s12
	v_or_b32_e32 v39, 0x1780, v29
	s_nop 0
	v_mbcnt_lo_u32_b32 v37, s90, 0
	v_mbcnt_hi_u32_b32 v37, s91, v37
	v_mad_i32_i24 v36, v37, v38, s87
	s_mov_b64 exec, s[90:91]
	ds_write_b16 v36, v39
	s_mov_b64 exec, s[44:45]
	s_bcnt1_i32_b64 s12, s[90:91]
	s_mul_i32 s12, s12, s88
	s_add_i32 s87, s87, s12
	s_cmp_eq_u64 s[92:93], 0
	s_cbranch_scc1 .Lcmp2_done
; __device__ __forceinline__ void attn_item(const Ptrs& P, unsigned char* lds, int b, int tq0, int tid) {
;     ...
; #pragma unroll
;         for (int k = 0; k < 4; ++k) if (16 * k < nact) {
; #pragma unroll
;             for (int r = 16 * k; r < 16 * k + 16; ++r) { const unsigned short idx = (unsigned short)(64 * (2 * r + hs) + lane);
;                 if (k2[r] > th) { sel[qs * 256 + pos_g] = idx; ++pos_g; }
;                 if (any_eq) { if (k2[r] == th) { if (pos_e < quota) sel[qs * 256 + tot_gt + pos_e] = idx; ++pos_e; } } } }
	v_cmp_ge_u32_e64 s[78:79], v0, v5
	v_cmp_ge_u32_e64 s[90:91], v20, v5
	v_or_b32_e32 v39, 0x1800, v29
	v_mbcnt_lo_u32_b32 v37, s78, 0
	v_mbcnt_hi_u32_b32 v37, s79, v37
	v_mad_i32_i24 v36, v37, v38, s87
	s_mov_b64 exec, s[78:79]
	ds_write_b16 v36, v39
	s_mov_b64 exec, s[44:45]
	s_bcnt1_i32_b64 s12, s[78:79]
	s_mul_i32 s12, s12, s88
	s_add_i32 s87, s87, s12
	v_cmp_ge_u32_e64 s[78:79], v19, v5
	v_or_b32_e32 v39, 0x1880, v29
	v_mbcnt_lo_u32_b32 v37, s90, 0
	v_mbcnt_hi_u32_b32 v37, s91, v37
	v_mad_i32_i24 v36, v37, v38, s87
	s_mov_b64 exec, s[90:91]
	ds_write_b16 v36, v39
	s_mov_b64 exec, s[44:45]
	s_bcnt1_i32_b64 s12, s[90:91]
	s_mul_i32 s12, s12, s88
	s_add_i32 s87, s87, s12
	v_cmp_ge_u32_e64 s[90:91], v18, v5
	v_or_b32_e32 v39, 0x1900, v29
	v_mbcnt_lo_u32_b32 v37, s78, 0
	v_mbcnt_hi_u32_b32 v37, s79, v37
	v_mad_i32_i24 v36, v37, v38, s87
	s_mov_b64 exec, s[78:79]
	ds_write_b16 v36, v39
	s_mov_b64 exec, s[44:45]
	s_bcnt1_i32_b64 s12, s[78:79]
	s_mul_i32 s12, s12, s88
	s_add_i32 s87, s87, s12
	v_cmp_ge_u32_e64 s[78:79], v17, v5
	v_or_b32_e32 v39, 0x1980, v29
	v_mbcnt_lo_u32_b32 v37, s90, 0
	v_mbcnt_hi_u32_b32 v37, s91, v37
	v_mad_i32_i24 v36, v37, v38, s87
	s_mov_b64 exec, s[90:91]
	ds_write_b16 v36, v39
	s_mov_b64 exec, s[44:45]
	s_bcnt1_i32_b64 s12, s[90:91]
	s_mul_i32 s12, s12, s88
	s_add_i32 s87, s87, s12
	v_cmp_ge_u32_e64 s[90:91], v16, v5
	v_or_b32_e32 v39, 0x1a00, v29
	v_mbcnt_lo_u32_b32 v37, s78, 0
	v_mbcnt_hi_u32_b32 v37, s79, v37
	v_mad_i32_i24 v36, v37, v38, s87
	s_mov_b64 exec, s[78:79]
	ds_write_b16 v36, v39
	s_mov_b64 exec, s[44:45]
	s_bcnt1_i32_b64 s12, s[78:79]
	s_mul_i32 s12, s12, s88
	s_add_i32 s87, s87, s12
	v_cmp_ge_u32_e64 s[78:79], v15, v5
	v_or_b32_e32 v39, 0x1a80, v29
	v_mbcnt_lo_u32_b32 v37, s90, 0
	v_mbcnt_hi_u32_b32 v37, s91, v37
	v_mad_i32_i24 v36, v37, v38, s87
	s_mov_b64 exec, s[90:91]
	ds_write_b16 v36, v39
	s_mov_b64 exec, s[44:45]
	s_bcnt1_i32_b64 s12, s[90:91]
	s_mul_i32 s12, s12, s88
	s_add_i32 s87, s87, s12
	v_cmp_ge_u32_e64 s[90:91], v14, v5
	v_or_b32_e32 v39, 0x1b00, v29
	v_mbcnt_lo_u32_b32 v37, s78, 0
	v_mbcnt_hi_u32_b32 v37, s79, v37
	v_mad_i32_i24 v36, v37, v38, s87
	s_mov_b64 exec, s[78:79]
	ds_write_b16 v36, v39
	s_mov_b64 exec, s[44:45]
	s_bcnt1_i32_b64 s12, s[78:79]
	s_mul_i32 s12, s12, s88
	s_add_i32 s87, s87, s12
	v_cmp_ge_u32_e64 s[78:79], v13, v5
	v_or_b32_e32 v39, 0x1b80, v29
	v_mbcnt_lo_u32_b32 v37, s90, 0
	v_mbcnt_hi_u32_b32 v37, s91, v37
	v_mad_i32_i24 v36, v37, v38, s87
	s_mov_b64 exec, s[90:91]
	ds_write_b16 v36, v39
	s_mov_b64 exec, s[44:45]
	s_bcnt1_i32_b64 s12, s[90:91]
	s_mul_i32 s12, s12, s88
	s_add_i32 s87, s87, s12
	v_cmp_ge_u32_e64 s[90:91], v12, v5
	v_or_b32_e32 v39, 0x1c00, v29
	v_mbcnt_lo_u32_b32 v37, s78, 0
	v_mbcnt_hi_u32_b32 v37, s79, v37
	v_mad_i32_i24 v36, v37, v38, s87
	s_mov_b64 exec, s[78:79]
	ds_write_b16 v36, v39
	s_mov_b64 exec, s[44:45]
	s_bcnt1_i32_b64 s12, s[78:79]
	s_mul_i32 s12, s12, s88
	s_add_i32 s87, s87, s12
	v_cmp_ge_u32_e64 s[78:79], v11, v5
	v_or_b32_e32 v39, 0x1c80, v29
	v_mbcnt_lo_u32_b32 v37, s90, 0
	v_mbcnt_hi_u32_b32 v37, s91, v37
	v_mad_i32_i24 v36, v37, v38, s87
	s_mov_b64 exec, s[90:91]
	ds_write_b16 v36, v39
	s_mov_b64 exec, s[44:45]
	s_bcnt1_i32_b64 s12, s[90:91]
	s_mul_i32 s12, s12, s88
	s_add_i32 s87, s87, s12
	v_cmp_ge_u32_e64 s[90:91], v10, v5
	v_or_b32_e32 v39, 0x1d00, v29
	v_mbcnt_lo_u32_b32 v37, s78, 0
	v_mbcnt_hi_u32_b32 v37, s79, v37
	v_mad_i32_i24 v36, v37, v38, s87
	s_mov_b64 exec, s[78:79]
	ds_write_b16 v36, v39
	s_mov_b64 exec, s[44:45]
	s_bcnt1_i32_b64 s12, s[78:79]
	s_mul_i32 s12, s12, s88
	s_add_i32 s87, s87, s12
	v_cmp_ge_u32_e64 s[78:79], v9, v5
	v_or_b32_e32 v39, 0x1d80, v29
	v_mbcnt_lo_u32_b32 v37, s90, 0
	v_mbcnt_hi_u32_b32 v37, s91, v37
	v_mad_i32_i24 v36, v37, v38, s87
	s_mov_b64 exec, s[90:91]
	ds_write_b16 v36, v39
	s_mov_b64 exec, s[44:45]
	s_bcnt1_i32_b64 s12, s[90:91]
	s_mul_i32 s12, s12, s88
	s_add_i32 s87, s87, s12
	v_cmp_ge_u32_e64 s[90:91], v8, v5
	v_or_b32_e32 v39, 0x1e00, v29
	v_mbcnt_lo_u32_b32 v37, s78, 0
	v_mbcnt_hi_u32_b32 v37, s79, v37
	v_mad_i32_i24 v36, v37, v38, s87
	s_mov_b64 exec, s[78:79]
	ds_write_b16 v36, v39
	s_mov_b64 exec, s[44:45]
	s_bcnt1_i32_b64 s12, s[78:79]
	s_mul_i32 s12, s12, s88
	s_add_i32 s87, s87, s12
	v_cmp_ge_u32_e64 s[78:79], v7, v5
	v_or_b32_e32 v39, 0x1e80, v29
	v_mbcnt_lo_u32_b32 v37, s90, 0
	v_mbcnt_hi_u32_b32 v37, s91, v37
	v_mad_i32_i24 v36, v37, v38, s87
	s_mov_b64 exec, s[90:91]
	ds_write_b16 v36, v39
	s_mov_b64 exec, s[44:45]
	s_bcnt1_i32_b64 s12, s[90:91]
	s_mul_i32 s12, s12, s88
	s_add_i32 s87, s87, s12
	v_cmp_ge_u32_e64 s[90:91], v3, v5
	v_or_b32_e32 v39, 0x1f00, v29
	v_mbcnt_lo_u32_b32 v37, s78, 0
	v_mbcnt_hi_u32_b32 v37, s79, v37
	v_mad_i32_i24 v36, v37, v38, s87
	s_mov_b64 exec, s[78:79]
	ds_write_b16 v36, v39
	s_mov_b64 exec, s[44:45]
	s_bcnt1_i32_b64 s12, s[78:79]
	s_mul_i32 s12, s12, s88
	s_add_i32 s87, s87, s12
	v_or_b32_e32 v39, 0x1f80, v29
	s_nop 0
	v_mbcnt_lo_u32_b32 v37, s90, 0
	v_mbcnt_hi_u32_b32 v37, s91, v37
	v_mad_i32_i24 v36, v37, v38, s87
	s_mov_b64 exec, s[90:91]
	ds_write_b16 v36, v39
	s_mov_b64 exec, s[44:45]
	s_bcnt1_i32_b64 s12, s[90:91]
	s_mul_i32 s12, s12, s88
	s_add_i32 s87, s87, s12
; __device__ __forceinline__ void attn_item(const Ptrs& P, unsigned char* lds, int b, int tq0, int tid) {
;     ...
;         unsigned cg = 0, ce = 0;
; #pragma unroll
;         for (int k = 0; k < 4; ++k) if (16 * k < nact) {
; #pragma unroll
;             for (int r = 16 * k; r < 16 * k + 16; ++r) { cg += (k2[r] > th) ? 1u : 0u; ce += (k2[r] == th) ? 1u : 0u; } }
.Lcmp2_done:
	s_mov_b64 vcc, s[92:93]
	s_branch .LBB0_908
	s_nop 0
	s_nop 0
	s_nop 0
	s_nop 0
	s_nop 0
	s_nop 0
	s_nop 0
	s_nop 0
	s_nop 0
	s_nop 0
	s_nop 0
	s_nop 0
	s_nop 0
.Lcmp_slow:
	s_nop 0
	s_nop 0
	s_nop 0
	s_nop 0
	s_nop 0
	s_nop 0
	s_nop 0
	s_nop 0
	s_nop 0
	s_or_b64 exec, exec, s[72:73]
	v_mov_b32_e32 v25, 0
	v_mov_b32_e32 v26, 0
	s_and_saveexec_b64 s[44:45], s[18:19]
	s_cbranch_execz .LBB0_507
	v_cmp_gt_u32_e64 s[12:13], v95, v5
	s_nop 1
	v_cndmask_b32_e64 v24, 0, 1, s[12:13]
	v_cmp_gt_u32_e64 s[12:13], v6, v5
	s_nop 1
	v_addc_co_u32_e64 v24, s[12:13], 0, v24, s[12:13]
	v_cmp_eq_u32_e64 s[12:13], v95, v5
	s_nop 1
	v_cndmask_b32_e64 v25, 0, 1, s[12:13]
	v_cmp_eq_u32_e64 s[12:13], v6, v5
	s_nop 1
	v_addc_co_u32_e64 v25, s[12:13], 0, v25, s[12:13]
	v_cmp_gt_u32_e64 s[12:13], v94, v5
	s_nop 1
	v_cndmask_b32_e64 v26, 0, 1, s[12:13]
	v_cmp_eq_u32_e64 s[12:13], v94, v5
	s_nop 1
	v_cndmask_b32_e64 v27, 0, 1, s[12:13]
	v_cmp_gt_u32_e64 s[12:13], v93, v5
	s_nop 1
	v_addc_co_u32_e64 v24, s[12:13], v24, v26, s[12:13]
	v_cmp_eq_u32_e64 s[12:13], v93, v5
	s_nop 1
	v_addc_co_u32_e64 v25, s[12:13], v25, v27, s[12:13]
	v_cmp_gt_u32_e64 s[12:13], v92, v5
	s_nop 1
	v_cndmask_b32_e64 v26, 0, 1, s[12:13]
	v_cmp_eq_u32_e64 s[12:13], v92, v5
	s_nop 1
	v_cndmask_b32_e64 v27, 0, 1, s[12:13]
	v_cmp_gt_u32_e64 s[12:13], v91, v5
	s_nop 1
	v_addc_co_u32_e64 v24, s[12:13], v24, v26, s[12:13]
	v_cmp_eq_u32_e64 s[12:13], v91, v5
	s_nop 1
	v_addc_co_u32_e64 v25, s[12:13], v25, v27, s[12:13]
	v_cmp_gt_u32_e64 s[12:13], v90, v5
	s_nop 1
	v_cndmask_b32_e64 v26, 0, 1, s[12:13]
	v_cmp_eq_u32_e64 s[12:13], v90, v5
	s_nop 1
	v_cndmask_b32_e64 v27, 0, 1, s[12:13]
	v_cmp_gt_u32_e64 s[12:13], v89, v5
	s_nop 1
	v_addc_co_u32_e64 v24, s[12:13], v24, v26, s[12:13]
	v_cmp_eq_u32_e64 s[12:13], v89, v5
	s_nop 1
	v_addc_co_u32_e64 v25, s[12:13], v25, v27, s[12:13]
	v_cmp_gt_u32_e64 s[12:13], v88, v5
	s_nop 1
	v_cndmask_b32_e64 v26, 0, 1, s[12:13]
	v_cmp_eq_u32_e64 s[12:13], v88, v5
	s_nop 1
	v_cndmask_b32_e64 v27, 0, 1, s[12:13]
	v_cmp_gt_u32_e64 s[12:13], v87, v5
	s_nop 1
	v_addc_co_u32_e64 v24, s[12:13], v24, v26, s[12:13]
	v_cmp_eq_u32_e64 s[12:13], v87, v5
	s_nop 1
	v_addc_co_u32_e64 v25, s[12:13], v25, v27, s[12:13]
	v_cmp_gt_u32_e64 s[12:13], v86, v5
	s_nop 1
	v_cndmask_b32_e64 v26, 0, 1, s[12:13]
	v_cmp_eq_u32_e64 s[12:13], v86, v5
	s_nop 1
	v_cndmask_b32_e64 v27, 0, 1, s[12:13]
	v_cmp_gt_u32_e64 s[12:13], v85, v5
	s_nop 1
	v_addc_co_u32_e64 v24, s[12:13], v24, v26, s[12:13]
	v_cmp_eq_u32_e64 s[12:13], v85, v5
	s_nop 1
	v_addc_co_u32_e64 v25, s[12:13], v25, v27, s[12:13]
	v_cmp_gt_u32_e64 s[12:13], v84, v5
	s_nop 1
	v_cndmask_b32_e64 v26, 0, 1, s[12:13]
	v_cmp_eq_u32_e64 s[12:13], v84, v5
	s_nop 1
	v_cndmask_b32_e64 v27, 0, 1, s[12:13]
	v_cmp_gt_u32_e64 s[12:13], v83, v5
	s_nop 1
	v_addc_co_u32_e64 v24, s[12:13], v24, v26, s[12:13]
	v_cmp_eq_u32_e64 s[12:13], v83, v5
	s_nop 1
	v_addc_co_u32_e64 v25, s[12:13], v25, v27, s[12:13]
	v_cmp_gt_u32_e64 s[12:13], v82, v5
	s_nop 1
	v_cndmask_b32_e64 v26, 0, 1, s[12:13]
	v_cmp_eq_u32_e64 s[12:13], v82, v5
	s_nop 1
	v_cndmask_b32_e64 v27, 0, 1, s[12:13]
	v_cmp_gt_u32_e64 s[12:13], v81, v5
	s_nop 1
	v_addc_co_u32_e64 v26, s[12:13], v24, v26, s[12:13]
	v_cmp_eq_u32_e64 s[12:13], v81, v5
	s_nop 1
	v_addc_co_u32_e64 v25, s[12:13], v25, v27, s[12:13]
	s_or_b64 exec, exec, s[44:45]
	s_and_saveexec_b64 s[44:45], s[16:17]
	s_cbranch_execnz .LBB0_508

; #define PAIR_XCHG(SLOT, TAG, MINE, OTHER) do { const unsigned tg_ = (seq << 8) | (unsigned)(TAG); if (lane == 0) xw[w * 4 + (SLOT)] = ((MINE) << 16) | tg_; \
;             unsigned v_; do { v_ = xw[(w ^ 1) * 4 + (SLOT)]; } while ((v_ & 0xffffu) != tg_); OTHER = v_ >> 16; } while (0)
; __device__ __forceinline__ void attn_item(const Ptrs& P, unsigned char* lds, int b, int tq0, int tid) {
;     ...
;         { unsigned dn_; PAIR_XCHG(0, 42, 0u, dn_); (void)dn_; }
.LBB0_908:
	s_or_b64 exec, exec, s[14:15]
	v_or_b32_e32 v0, 42, v1
	s_and_saveexec_b64 s[12:13], s[4:5]
	s_cbranch_execz .LBB0_910
	s_lshl_b32 s14, s83, 2
	s_add_i32 s14, s14, 0
	s_add_i32 s14, s14, 0x24008
	v_mov_b32_e32 v2, s14
	v_mov_b32_e32 v3, s21
	ds_write_b32 v2, v0
	s_waitcnt vmcnt(0) lgkmcnt(0)
.LBB0_910:
	s_or_b64 exec, exec, s[12:13]
	s_add_i32 s73, s72, 8
	s_mov_b64 s[12:13], 0
.LBB0_911:
	v_mov_b32_e32 v2, s73
	ds_read_b32 v1, v2
	s_waitcnt vmcnt(0) lgkmcnt(0)
	v_cmp_eq_u32_sdwa s[14:15], v1, v0 src0_sel:WORD_0 src1_sel:DWORD
	s_or_b64 s[12:13], s[14:15], s[12:13]
	s_andn2_b64 exec, exec, s[12:13]
	s_cbranch_execnz .LBB0_911
	s_or_b64 exec, exec, s[12:13]
